# bias-row gemv items of the conversion phase moved to workgroups 80..255 (the workgroups with a ninth row-conversion pass and the transposes no longer also run a gemv)
# baseline (speedup 1.0000x reference)
.LBB0_1429:
	s_mov_b32 s12, s80
	s_cmp_lg_u32 s25, 0x100
	s_cbranch_scc1 .Lp1_keep
	s_sub_i32 s12, s80, 0x50
	s_cmp_lt_i32 s12, 0
	s_cbranch_scc1 .LBB0_1430
.Lp1_keep:
	s_cmpk_gt_i32 s12, 0xaf
	s_cbranch_scc0 .LBB0_1453
